# attention: LDS-DMA with SGPR base (no per-piece 64-bit VALU add), redundant canonicalising max ops removed
# speedup vs baseline: 1.0089x; 1.0089x over previous
; template <int DQK>
; __device__ __forceinline__ void attn_pass4(LAS unsigned char* lds, const bf16* Qp, int qpitch, const bf16* Kp, int kpitch, const bf16* Vp, int vpitch, int q0, f32x16 (&o)[4], float (&rl)[16]) {
;     ...
;     if (!shifted) {
;         for (int t = 0; t < NT; ++t) {
;             const int vnext = ATT_VNEXT(vcur);
;             if (t + 1 < NT) ATT_DMA(t + 1, (t + 1) & 1, vnext);
.LBB0_621:
	s_add_i32 s25, s24, 1
	s_cmp_lg_u32 s24, 2
	s_cselect_b32 s35, s25, 0
	s_add_i32 s25, s72, 1
	s_cmp_ge_u32 s25, s31
	s_cbranch_scc1 .LBB0_625
	s_bitcmp1_b32 s25, 0
	s_cselect_b32 s73, 0x2400, 0
	s_add_i32 s74, s73, s5

; __device__ __forceinline__ void glds16(const void* gsrc, unsigned lds_dst) { unsigned keep;
;     asm volatile("s_mov_b32 %0, m0\n\ts_mov_b32 m0, %2\n\ts_nop 0\n\tglobal_load_lds_dwordx4 %1, off\n\ts_mov_b32 m0, %0" : "=&s"(keep) : "v"(gsrc), "s"(lds_dst) : "memory"); }
	s_add_i32 s74, s74, 0
	s_mov_b32 s75, m0
	s_mov_b32 m0, s74
	s_nop 0
	global_load_lds_dwordx4 v170, s[70:71]
	s_mov_b32 m0, s75
	s_andn2_b64 vcc, exec, s[10:11]
	s_cbranch_vccnz .LBB0_624
	s_add_i32 s73, s73, s80

; __device__ __forceinline__ void glds16(const void* gsrc, unsigned lds_dst) { unsigned keep;
;     asm volatile("s_mov_b32 %0, m0\n\ts_mov_b32 m0, %2\n\ts_nop 0\n\tglobal_load_lds_dwordx4 %1, off\n\ts_mov_b32 m0, %0" : "=&s"(keep) : "v"(gsrc), "s"(lds_dst) : "memory"); }
	s_add_i32 s73, s73, 0
	s_mov_b32 s74, m0
	s_mov_b32 m0, s73
	s_nop 0
	global_load_lds_dwordx4 v176, s[70:71]
	s_mov_b32 m0, s74
.LBB0_624:
	s_add_u32 s74, s70, 0x4000000
	s_mul_i32 s73, s35, 0x5000
	s_addc_u32 s75, s71, 0
	s_add_i32 s73, s26, s73

; __device__ __forceinline__ void glds16(const void* gsrc, unsigned lds_dst) { unsigned keep;
;     asm volatile("s_mov_b32 %0, m0\n\ts_mov_b32 m0, %2\n\ts_nop 0\n\tglobal_load_lds_dwordx4 %1, off\n\ts_mov_b32 m0, %0" : "=&s"(keep) : "v"(gsrc), "s"(lds_dst) : "memory"); }
	s_add_i32 s73, s73, 0
	s_mov_b32 vcc_lo, m0
	s_mov_b32 m0, s73
	s_nop 0
	global_load_lds_dwordx4 v172, s[74:75]
	s_mov_b32 m0, vcc_lo
	s_add_i32 vcc_lo, s73, 0x2000

; __device__ __forceinline__ void glds16(const void* gsrc, unsigned lds_dst) { unsigned keep;
;     asm volatile("s_mov_b32 %0, m0\n\ts_mov_b32 m0, %2\n\ts_nop 0\n\tglobal_load_lds_dwordx4 %1, off\n\ts_mov_b32 m0, %0" : "=&s"(keep) : "v"(gsrc), "s"(lds_dst) : "memory"); }
	s_mov_b32 vcc_hi, m0
	s_mov_b32 m0, vcc_lo
	s_nop 0
	global_load_lds_dwordx4 v174, s[74:75]
	s_mov_b32 m0, vcc_hi
	v_readfirstlane_b32 s32, v242
	s_cmpk_gt_u32 s32, 0xff
	s_cbranch_scc1 .Lskip_v2_0
	v_lshl_add_u64 v[114:115], s[74:75], 0, v[178:179]
	s_addk_i32 s73, 0x4000
	s_mov_b32 s74, m0
	s_mov_b32 m0, s73
	s_nop 0
	global_load_lds_dwordx4 v[114:115], off
	s_mov_b32 m0, s74

.LBB0_628:
	s_nop 5
	v_max_f32_e32 v32, v114, v115


; __device__ __forceinline__ float xhalf_max(float m) { auto rr = __builtin_amdgcn_permlane32_swap(__float_as_uint(m), __float_as_uint(m), false, false); return fmaxf(__uint_as_float(rr[0]), __uint_as_float(rr[1])); }
	v_max3_f32 v198, v116, v117, v131
	v_max3_f32 v32, v32, v130, v132
	v_max3_f32 v32, v32, v133, v118
	v_max3_f32 v198, v198, v120, v121
	v_max3_f32 v32, v32, v119, v134
	v_max3_f32 v198, v198, v136, v137
	v_max3_f32 v32, v32, v135, v122
	v_max3_f32 v198, v198, v124, v125
	v_max3_f32 v32, v32, v123, v138
	v_max3_f32 v198, v198, v140, v141
	v_max3_f32 v32, v32, v139, v126
	v_max3_f32 v198, v198, v128, v129
	v_max3_f32 v32, v32, v127, v142
	v_max3_f32 v198, v198, v144, v145
	v_max3_f32 v32, v32, v143, v198
	v_mov_b32_e32 v198, v32
	s_nop 1
	v_permlane32_swap_b32_e32 v32, v198


	s_cmp_lg_u32 s18, 63
	v_max_f32_e32 v32, v32, v198
	s_cselect_b64 s[72:73], -1, 0
	s_cmp_eq_u32 s18, 63
	s_mov_b64 s[74:75], -1
	s_cbranch_scc1 .LBB0_631
	v_cmp_lt_f32_e32 vcc, s83, v32
	s_cbranch_vccz .LBB0_640
	v_max_f32_e32 v32, v32, v32
	v_max_f32_e32 v32, 0, v32

; template <int DQK>
; __device__ __forceinline__ void attn_pass4(LAS unsigned char* lds, const bf16* Qp, int qpitch, const bf16* Kp, int kpitch, const bf16* Vp, int vpitch, int q0, f32x16 (&o)[4], float (&rl)[16]) {
;     ...
;     if (!shifted) {
;         for (int t = 0; t < NT; ++t) {
;             const int vnext = ATT_VNEXT(vcur);
;             if (t + 1 < NT) ATT_DMA(t + 1, (t + 1) & 1, vnext);
.LBB0_821:
	s_add_i32 s24, s35, 1
	s_cmp_lg_u32 s35, 2
	s_cselect_b32 s24, s24, 0
	s_add_i32 s25, s72, 1
	s_cmp_ge_u32 s25, s31
	s_cbranch_scc1 .LBB0_825
	s_bitcmp1_b32 s25, 0
	s_cselect_b32 s73, 0x2400, 0
	s_add_i32 s74, s73, s3

; __device__ __forceinline__ void glds16(const void* gsrc, unsigned lds_dst) { unsigned keep;
;     asm volatile("s_mov_b32 %0, m0\n\ts_mov_b32 m0, %2\n\ts_nop 0\n\tglobal_load_lds_dwordx4 %1, off\n\ts_mov_b32 m0, %0" : "=&s"(keep) : "v"(gsrc), "s"(lds_dst) : "memory"); }
	s_add_i32 s74, s74, 0
	s_mov_b32 s75, m0
	s_mov_b32 m0, s74
	s_nop 0
	global_load_lds_dwordx4 v170, s[70:71]
	s_mov_b32 m0, s75
	s_andn2_b64 vcc, exec, s[10:11]
	s_cbranch_vccnz .LBB0_824
	s_add_i32 s73, s73, s27

; __device__ __forceinline__ void glds16(const void* gsrc, unsigned lds_dst) { unsigned keep;
;     asm volatile("s_mov_b32 %0, m0\n\ts_mov_b32 m0, %2\n\ts_nop 0\n\tglobal_load_lds_dwordx4 %1, off\n\ts_mov_b32 m0, %0" : "=&s"(keep) : "v"(gsrc), "s"(lds_dst) : "memory"); }
	s_add_i32 s73, s73, 0
	s_mov_b32 s74, m0
	s_mov_b32 m0, s73
	s_nop 0
	global_load_lds_dwordx4 v176, s[70:71]
	s_mov_b32 m0, s74
.LBB0_824:
	s_add_u32 s74, s70, 0x3ffff80
	s_mul_i32 s73, s24, 0x5000
	s_addc_u32 s75, s71, 0
	s_add_i32 s73, s5, s73

; __device__ __forceinline__ void glds16(const void* gsrc, unsigned lds_dst) { unsigned keep;
;     asm volatile("s_mov_b32 %0, m0\n\ts_mov_b32 m0, %2\n\ts_nop 0\n\tglobal_load_lds_dwordx4 %1, off\n\ts_mov_b32 m0, %0" : "=&s"(keep) : "v"(gsrc), "s"(lds_dst) : "memory"); }
	s_add_i32 s73, s73, 0
	s_mov_b32 vcc_lo, m0
	s_mov_b32 m0, s73
	s_nop 0
	global_load_lds_dwordx4 v172, s[74:75]
	s_mov_b32 m0, vcc_lo
	s_add_i32 vcc_lo, s73, 0x2000

; __device__ __forceinline__ void glds16(const void* gsrc, unsigned lds_dst) { unsigned keep;
;     asm volatile("s_mov_b32 %0, m0\n\ts_mov_b32 m0, %2\n\ts_nop 0\n\tglobal_load_lds_dwordx4 %1, off\n\ts_mov_b32 m0, %0" : "=&s"(keep) : "v"(gsrc), "s"(lds_dst) : "memory"); }
	s_mov_b32 vcc_hi, m0
	s_mov_b32 m0, vcc_lo
	s_nop 0
	global_load_lds_dwordx4 v174, s[74:75]
	s_mov_b32 m0, vcc_hi
	v_readfirstlane_b32 s32, v242
	s_cmpk_gt_u32 s32, 0xff
	s_cbranch_scc1 .Lskip_v2_1
	v_lshl_add_u64 v[114:115], s[74:75], 0, v[178:179]
	s_addk_i32 s73, 0x4000
	s_mov_b32 s74, m0
	s_mov_b32 m0, s73
	s_nop 0
	global_load_lds_dwordx4 v[114:115], off
	s_mov_b32 m0, s74

; template <int DQK>
; __device__ __forceinline__ void attn_pass4(LAS unsigned char* lds, const bf16* Qp, int qpitch, const bf16* Kp, int kpitch, const bf16* Vp, int vpitch, int q0, f32x16 (&o)[4], float (&rl)[16]) {
;     ...
;     if (!shifted) {
;         for (int t = 0; t < NT; ++t) {
;             const int vnext = ATT_VNEXT(vcur);
;             if (t + 1 < NT) ATT_DMA(t + 1, (t + 1) & 1, vnext);
.LBB0_2151:
	s_add_i32 s61, s78, 1
	s_cmp_lg_u32 s78, 2
	s_cselect_b32 s76, s61, 0
	s_add_i32 s77, s60, 1
	s_cmp_ge_u32 s77, s69
	s_cbranch_scc1 .LBB0_2155
	s_bitcmp1_b32 s77, 0
	s_cselect_b32 s61, 0x6400, 0
	s_add_i32 s62, s61, s2
	s_add_i32 s62, s62, 0

; __device__ __forceinline__ void glds16(const void* gsrc, unsigned lds_dst) { unsigned keep;
;     asm volatile("s_mov_b32 %0, m0\n\ts_mov_b32 m0, %2\n\ts_nop 0\n\tglobal_load_lds_dwordx4 %1, off\n\ts_mov_b32 m0, %0" : "=&s"(keep) : "v"(gsrc), "s"(lds_dst) : "memory"); }
	s_mov_b32 s63, m0
	s_mov_b32 m0, s62
	s_nop 0
	global_load_lds_dwordx4 v180, s[56:57]
	s_mov_b32 m0, s63
	s_add_i32 s62, s61, s72
	s_add_i32 s62, s62, 0

; __device__ __forceinline__ void glds16(const void* gsrc, unsigned lds_dst) { unsigned keep;
;     asm volatile("s_mov_b32 %0, m0\n\ts_mov_b32 m0, %2\n\ts_nop 0\n\tglobal_load_lds_dwordx4 %1, off\n\ts_mov_b32 m0, %0" : "=&s"(keep) : "v"(gsrc), "s"(lds_dst) : "memory"); }
	s_mov_b32 s63, m0
	s_mov_b32 m0, s62
	s_nop 0
	global_load_lds_dwordx4 v182, s[56:57]
	s_mov_b32 m0, s63
	s_add_i32 s62, s61, s73

; __device__ __forceinline__ void glds16(const void* gsrc, unsigned lds_dst) { unsigned keep;
;     asm volatile("s_mov_b32 %0, m0\n\ts_mov_b32 m0, %2\n\ts_nop 0\n\tglobal_load_lds_dwordx4 %1, off\n\ts_mov_b32 m0, %0" : "=&s"(keep) : "v"(gsrc), "s"(lds_dst) : "memory"); }
	s_add_i32 s62, s62, 0
	s_mov_b32 s63, m0
	s_mov_b32 m0, s62
	s_nop 0
	global_load_lds_dwordx4 v184, s[56:57]
	s_mov_b32 m0, s63
	s_andn2_b64 vcc, exec, s[12:13]
	s_cbranch_vccnz .LBB0_2154
	s_add_i32 s61, s61, s74

; __device__ __forceinline__ void glds16(const void* gsrc, unsigned lds_dst) { unsigned keep;
;     asm volatile("s_mov_b32 %0, m0\n\ts_mov_b32 m0, %2\n\ts_nop 0\n\tglobal_load_lds_dwordx4 %1, off\n\ts_mov_b32 m0, %0" : "=&s"(keep) : "v"(gsrc), "s"(lds_dst) : "memory"); }
	s_add_i32 s61, s61, 0
	s_mov_b32 s62, m0
	s_mov_b32 m0, s61
	s_nop 0
	global_load_lds_dwordx4 v190, s[56:57]
	s_mov_b32 m0, s62
.LBB0_2154:
	s_mul_i32 s61, s76, 0x5000
	s_add_i32 s61, s24, s61

; __device__ __forceinline__ void glds16(const void* gsrc, unsigned lds_dst) { unsigned keep;
;     asm volatile("s_mov_b32 %0, m0\n\ts_mov_b32 m0, %2\n\ts_nop 0\n\tglobal_load_lds_dwordx4 %1, off\n\ts_mov_b32 m0, %0" : "=&s"(keep) : "v"(gsrc), "s"(lds_dst) : "memory"); }
	s_add_i32 s61, s61, 0
	s_mov_b32 s62, m0
	s_mov_b32 m0, s61
	s_nop 0
	global_load_lds_dwordx4 v186, s[58:59]
	s_mov_b32 m0, s62

; __device__ __forceinline__ void glds16(const void* gsrc, unsigned lds_dst) { unsigned keep;
;     asm volatile("s_mov_b32 %0, m0\n\ts_mov_b32 m0, %2\n\ts_nop 0\n\tglobal_load_lds_dwordx4 %1, off\n\ts_mov_b32 m0, %0" : "=&s"(keep) : "v"(gsrc), "s"(lds_dst) : "memory"); }
	s_add_i32 s62, s61, 0x2000
	s_mov_b32 s63, m0
	s_mov_b32 m0, s62
	s_nop 0
	global_load_lds_dwordx4 v188, s[58:59]
	s_mov_b32 m0, s63
	v_readfirstlane_b32 s32, v242
	s_cmpk_gt_u32 s32, 0xff
	s_cbranch_scc1 .Lskip_v2_2

; __device__ __forceinline__ void glds16(const void* gsrc, unsigned lds_dst) { unsigned keep;
;     asm volatile("s_mov_b32 %0, m0\n\ts_mov_b32 m0, %2\n\ts_nop 0\n\tglobal_load_lds_dwordx4 %1, off\n\ts_mov_b32 m0, %0" : "=&s"(keep) : "v"(gsrc), "s"(lds_dst) : "memory"); }
	s_addk_i32 s61, 0x4000
	s_mov_b32 s62, m0
	s_mov_b32 m0, s61
	s_nop 0
	global_load_lds_dwordx4 v192, s[58:59]
	s_mov_b32 m0, s62

.LBB0_2158:
	s_nop 6
	v_max_f32_e32 v0, v96, v97


; __device__ __forceinline__ float xhalf_max(float m) { auto rr = __builtin_amdgcn_permlane32_swap(__float_as_uint(m), __float_as_uint(m), false, false); return fmaxf(__uint_as_float(rr[0]), __uint_as_float(rr[1])); }
	v_max3_f32 v3, v98, v99, v113
	v_max3_f32 v0, v0, v112, v114
	v_max3_f32 v0, v0, v115, v100
	v_max3_f32 v3, v3, v102, v103
	v_max3_f32 v0, v0, v101, v116
	v_max3_f32 v3, v3, v118, v119
	v_max3_f32 v0, v0, v117, v104
	v_max3_f32 v3, v3, v106, v107
	v_max3_f32 v0, v0, v105, v120
	v_max3_f32 v3, v3, v122, v123
	v_max3_f32 v0, v0, v121, v108
	v_max3_f32 v3, v3, v110, v111
	v_max3_f32 v0, v0, v109, v124
	v_max3_f32 v3, v3, v126, v127
	v_max3_f32 v0, v0, v125, v3
	v_mov_b32_e32 v3, v0
	s_nop 1
	v_permlane32_swap_b32_e32 v0, v3


	s_cmp_lg_u32 s75, 63
	v_max_f32_e32 v0, v0, v3
	s_cselect_b64 s[60:61], -1, 0
	s_cmp_eq_u32 s75, 63
	s_mov_b64 s[62:63], -1
	s_cbranch_scc1 .LBB0_2161
	v_cmp_lt_f32_e32 vcc, s31, v0
	s_cbranch_vccz .LBB0_2170
	v_max_f32_e32 v0, v0, v0
	v_max_f32_e32 v0, 0, v0
